# v38 plus grid barriers G2-G7 rewritten by hand with a shorter release chain (last XCD bumps every XCD generation word directly)
# speedup vs baseline: 1.0035x; 1.0035x over previous
.LBB0_405:
	v_mbcnt_lo_u32_b32 v0, -1, 0
	v_mbcnt_hi_u32_b32 v0, -1, v0
	s_waitcnt vmcnt(0)
	v_readlane_b32 s0, v253, 11
	s_waitcnt vmcnt(0)
	s_barrier
	v_cmp_eq_u32_e32 vcc, s0, v0
	s_and_saveexec_b64 s[0:1], vcc
	s_cbranch_execz .LBB0_457
	s_waitcnt vmcnt(0) expcnt(0) lgkmcnt(0)
	v_mov_b32_e32 v0, 0x20000
	ds_read2_b32 v[4:5], v0 offset1:1
	v_readlane_b32 s14, v254, 8
	v_readlane_b32 s15, v254, 9
	v_mov_b32_e32 v1, 1
	s_nop 4
	global_atomic_add v2, v97, v1, s[14:15] sc0
	s_waitcnt vmcnt(0) lgkmcnt(0)
	v_cvt_f32_u32_e32 v6, v2
	v_cvt_f32_u32_e32 v7, v4
	v_add_f32_e32 v6, 0.5, v6
	v_rcp_f32_e32 v7, v7
	s_nop 0
	v_mul_f32_e32 v6, v6, v7
	v_cvt_u32_f32_e32 v6, v6
	v_add_u32_e32 v7, 1, v6
	v_mul_lo_u32 v7, v7, v4
	v_add_u32_e32 v8, 1, v2
	v_cmp_eq_u32_e32 vcc, v7, v8
	s_cbranch_vccz .Lxb_g2_wait
	buffer_wbl2 sc1
	v_readlane_b32 s14, v254, 12
	v_readlane_b32 s15, v254, 13
	s_waitcnt vmcnt(0)
	s_nop 4
	global_atomic_add v9, v97, v1, s[14:15] sc0
	s_waitcnt vmcnt(0)
	v_cvt_f32_u32_e32 v10, v9
	v_cvt_f32_u32_e32 v11, v5
	v_add_f32_e32 v10, 0.5, v10
	v_rcp_f32_e32 v11, v11
	s_nop 0
	v_mul_f32_e32 v10, v10, v11
	v_cvt_u32_f32_e32 v10, v10
	v_add_u32_e32 v10, 1, v10
	v_mul_lo_u32 v10, v10, v5
	v_add_u32_e32 v9, 1, v9
	v_cmp_eq_u32_e32 vcc, v10, v9
	s_cbranch_vccz .Lxb_g2_wait
	v_readlane_b32 s14, v254, 14
	v_readlane_b32 s15, v254, 15
	s_mov_b64 s[18:19], exec
	s_mov_b64 exec, 0xffff
	s_nop 1
	v_mbcnt_lo_u32_b32 v10, -1, 0
	v_mov_b32_e32 v11, 1
	v_lshlrev_b32_e32 v10, 8, v10
	v_add_u32_e32 v10, 0x2000, v10
	global_atomic_add v10, v11, s[68:69]
	s_mov_b64 exec, s[18:19]
	s_nop 1
	global_atomic_add v97, v1, s[14:15]
	s_branch .Lxb_g2_acq
.Lxb_g2_wait:
	v_readlane_b32 s14, v254, 10
	v_readlane_b32 s15, v254, 11
	s_mov_b32 s13, 0
	s_nop 4
.Lxb_g2_spin:
	global_load_dword v0, v97, s[14:15] sc1
	s_add_i32 s13, s13, 1
	s_waitcnt vmcnt(0)
	v_cmp_ne_u32_e32 vcc, v0, v6
	s_cbranch_vccnz .Lxb_g2_acq
	s_cmp_lt_u32 s13, 0x10000
	s_cbranch_scc0 .Lxb_g2_acq
	s_sleep 1
	s_branch .Lxb_g2_spin
.Lxb_g2_acq:
	buffer_inv sc1
	s_waitcnt vmcnt(0)
.LBB0_457:
	s_or_b64 exec, exec, s[0:1]
	s_lshl_b32 s48, s48, 7
	s_mov_b32 s0, 0
	s_mov_b32 s49, 0
	s_waitcnt lgkmcnt(0)
	s_barrier
	s_branch .LBB0_461

.LBB0_823:
	v_mbcnt_lo_u32_b32 v0, -1, 0
	v_mbcnt_hi_u32_b32 v0, -1, v0
	s_waitcnt vmcnt(0)
	v_readlane_b32 s0, v253, 11
	s_barrier
	s_nop 0
	v_cmp_eq_u32_e32 vcc, s0, v0
	s_and_saveexec_b64 s[0:1], vcc
	s_cbranch_execz .LBB0_875
	s_waitcnt vmcnt(0) expcnt(0) lgkmcnt(0)
	v_mov_b32_e32 v0, 0x20000
	ds_read2_b32 v[4:5], v0 offset1:1
	v_readlane_b32 s14, v254, 8
	v_readlane_b32 s15, v254, 9
	v_mov_b32_e32 v1, 1
	s_nop 4
	global_atomic_add v2, v97, v1, s[14:15] sc0
	s_waitcnt vmcnt(0) lgkmcnt(0)
	v_cvt_f32_u32_e32 v6, v2
	v_cvt_f32_u32_e32 v7, v4
	v_add_f32_e32 v6, 0.5, v6
	v_rcp_f32_e32 v7, v7
	s_nop 0
	v_mul_f32_e32 v6, v6, v7
	v_cvt_u32_f32_e32 v6, v6
	v_add_u32_e32 v7, 1, v6
	v_mul_lo_u32 v7, v7, v4
	v_add_u32_e32 v8, 1, v2
	v_cmp_eq_u32_e32 vcc, v7, v8
	s_cbranch_vccz .Lxb_g3_wait
	buffer_wbl2 sc1
	v_readlane_b32 s14, v254, 12
	v_readlane_b32 s15, v254, 13
	s_waitcnt vmcnt(0)
	s_nop 4
	global_atomic_add v9, v97, v1, s[14:15] sc0
	s_waitcnt vmcnt(0)
	v_cvt_f32_u32_e32 v10, v9
	v_cvt_f32_u32_e32 v11, v5
	v_add_f32_e32 v10, 0.5, v10
	v_rcp_f32_e32 v11, v11
	s_nop 0
	v_mul_f32_e32 v10, v10, v11
	v_cvt_u32_f32_e32 v10, v10
	v_add_u32_e32 v10, 1, v10
	v_mul_lo_u32 v10, v10, v5
	v_add_u32_e32 v9, 1, v9
	v_cmp_eq_u32_e32 vcc, v10, v9
	s_cbranch_vccz .Lxb_g3_wait
	v_readlane_b32 s14, v254, 14
	v_readlane_b32 s15, v254, 15
	s_mov_b64 s[18:19], exec
	s_mov_b64 exec, 0xffff
	s_nop 1
	v_mbcnt_lo_u32_b32 v10, -1, 0
	v_mov_b32_e32 v11, 1
	v_lshlrev_b32_e32 v10, 8, v10
	v_add_u32_e32 v10, 0x2000, v10
	global_atomic_add v10, v11, s[68:69]
	s_mov_b64 exec, s[18:19]
	s_nop 1
	global_atomic_add v97, v1, s[14:15]
	s_branch .Lxb_g3_acq

.Lxb_g3_acq:
	buffer_inv sc1
	s_waitcnt vmcnt(0)
.LBB0_875:
	s_or_b64 exec, exec, s[0:1]
	s_waitcnt lgkmcnt(0)
	s_barrier
	v_mbcnt_lo_u32_b32 v4, -1, 0
	v_mbcnt_hi_u32_b32 v4, -1, v4
	v_readlane_b32 s14, v253, 0
	v_add_u32_e32 v0, s65, v4
	v_readlane_b32 s50, v255, 48
	v_readfirstlane_b32 s0, v0
	s_ashr_i32 s18, s0, 6
	v_readlane_b32 s0, v253, 3
	s_add_i32 s12, s18, s0
	v_readlane_b32 s15, v253, 1
	s_cmpk_gt_i32 s12, 0x1fff
	v_readlane_b32 s51, v255, 49
	s_cbranch_scc1 .LBB0_890
	v_readlane_b32 s0, v255, 54
	v_and_b32_e32 v14, 63, v4
	s_cmp_lg_u32 s0, 0
	s_cselect_b64 s[0:1], -1, 0
	v_cmp_gt_u32_e32 vcc, 4, v14
	s_and_b64 s[22:23], s[0:1], vcc
	s_add_u32 s26, s14, 0x3d913000
	v_lshlrev_b32_e32 v0, 15, v4
	s_addc_u32 s54, s15, 0
	s_ashr_i32 s13, s12, 31
	v_and_b32_e32 v2, 1, v4
	v_and_b32_e32 v96, 0x10000, v0
	s_lshl_b64 s[36:37], s[12:13], 11
	v_lshl_add_u64 v[0:1], s[14:15], 0, v[96:97]
	v_lshlrev_b32_e32 v96, 2, v2
	s_lshl_b64 s[24:25], s[12:13], 2
	s_lshl_b32 s19, s18, 6
	v_readlane_b32 s34, v253, 4
	v_lshl_or_b32 v2, v14, 5, s36
	v_mov_b32_e32 v3, s37
	s_lshl_b64 s[36:37], s[12:13], 4
	s_mul_hi_i32 s13, s12, 0x1800
	v_lshl_add_u64 v[0:1], v[0:1], 0, v[96:97]
	s_mov_b64 s[0:1], 0x398a3000
	s_add_i32 s34, s34, s19
	v_lshrrev_b32_e32 v4, 2, v4
	s_mul_i32 s19, s12, 0x1800
	v_mov_b32_e32 v7, s13
	s_lshl_b32 s13, s18, 1
	v_readlane_b32 s18, v255, 24
	v_lshl_add_u64 v[0:1], v[0:1], 0, s[0:1]
	v_cmp_eq_u32_e64 s[0:1], 6, v14
	v_and_or_b32 v4, v4, 12, s36
	v_mov_b32_e32 v5, s37
	v_lshl_or_b32 v6, v14, 4, s19
	s_add_i32 s36, s18, s13
	s_branch .LBB0_878

.LBB0_890:
	v_mbcnt_lo_u32_b32 v0, -1, 0
	v_mbcnt_hi_u32_b32 v0, -1, v0
	s_waitcnt vmcnt(0)
	v_readlane_b32 s0, v253, 11
	s_waitcnt lgkmcnt(0)
	s_barrier
	v_cmp_eq_u32_e32 vcc, s0, v0
	s_and_saveexec_b64 s[0:1], vcc
	s_cbranch_execz .LBB0_942
	s_waitcnt vmcnt(0) expcnt(0) lgkmcnt(0)
	v_mov_b32_e32 v0, 0x20000
	ds_read2_b32 v[4:5], v0 offset1:1
	v_readlane_b32 s14, v254, 8
	v_readlane_b32 s15, v254, 9
	v_mov_b32_e32 v1, 1
	s_nop 4
	global_atomic_add v2, v97, v1, s[14:15] sc0
	s_waitcnt vmcnt(0) lgkmcnt(0)
	v_cvt_f32_u32_e32 v6, v2
	v_cvt_f32_u32_e32 v7, v4
	v_add_f32_e32 v6, 0.5, v6
	v_rcp_f32_e32 v7, v7
	s_nop 0
	v_mul_f32_e32 v6, v6, v7
	v_cvt_u32_f32_e32 v6, v6
	v_add_u32_e32 v7, 1, v6
	v_mul_lo_u32 v7, v7, v4
	v_add_u32_e32 v8, 1, v2
	v_cmp_eq_u32_e32 vcc, v7, v8
	s_cbranch_vccz .Lxb_g4_wait
	buffer_wbl2 sc1
	v_readlane_b32 s14, v254, 12
	v_readlane_b32 s15, v254, 13
	s_waitcnt vmcnt(0)
	s_nop 4
	global_atomic_add v9, v97, v1, s[14:15] sc0
	s_waitcnt vmcnt(0)
	v_cvt_f32_u32_e32 v10, v9
	v_cvt_f32_u32_e32 v11, v5
	v_add_f32_e32 v10, 0.5, v10
	v_rcp_f32_e32 v11, v11
	s_nop 0
	v_mul_f32_e32 v10, v10, v11
	v_cvt_u32_f32_e32 v10, v10
	v_add_u32_e32 v10, 1, v10
	v_mul_lo_u32 v10, v10, v5
	v_add_u32_e32 v9, 1, v9
	v_cmp_eq_u32_e32 vcc, v10, v9
	s_cbranch_vccz .Lxb_g4_wait
	v_readlane_b32 s14, v254, 14
	v_readlane_b32 s15, v254, 15
	s_mov_b64 s[18:19], exec
	s_mov_b64 exec, 0xffff
	s_nop 1
	v_mbcnt_lo_u32_b32 v10, -1, 0
	v_mov_b32_e32 v11, 1
	v_lshlrev_b32_e32 v10, 8, v10
	v_add_u32_e32 v10, 0x2000, v10
	global_atomic_add v10, v11, s[68:69]
	s_mov_b64 exec, s[18:19]
	s_nop 1
	global_atomic_add v97, v1, s[14:15]
	s_branch .Lxb_g4_acq

.Lxb_g4_acq:
	buffer_inv sc1
	s_waitcnt vmcnt(0)
.LBB0_942:
	s_or_b64 exec, exec, s[0:1]
	v_readlane_b32 s0, v254, 24
	v_readlane_b32 s1, v254, 25
	v_readlane_b32 s14, v253, 0
	v_readlane_b32 s15, v253, 1
	v_cndmask_b32_e64 v1, 0, 1, s[0:1]
	v_cmp_ne_u32_e64 s[12:13], 1, v1
	s_waitcnt lgkmcnt(0)
	s_barrier
	v_mbcnt_lo_u32_b32 v8, -1, 0
	v_mbcnt_hi_u32_b32 v8, -1, v8
	v_writelane_b32 v255, s12, 56
	v_add_u32_e32 v0, s65, v8
	s_andn2_b64 vcc, exec, s[0:1]
	v_writelane_b32 v255, s13, 57
	v_readfirstlane_b32 s18, v0
	s_cbranch_vccnz .LBB0_971
	v_lshlrev_b32_e32 v1, 4, v0
	v_add_u32_e32 v2, 0x2000, v1
	v_ashrrev_i32_e32 v3, 31, v2
	v_lshrrev_b32_e32 v3, 22, v3
	v_add_u32_e32 v3, v2, v3
	v_ashrrev_i32_e32 v3, 10, v3
	v_mul_i32_i24_e32 v4, 0x400, v3
	v_sub_u32_e32 v2, v2, v4
	v_lshrrev_b32_e32 v4, 4, v2
	v_bitop3_b32 v2, v4, v2, 32 bitop3:0x6c
	v_ashrrev_i32_e32 v4, 31, v2
	v_lshrrev_b32_e32 v4, 26, v4
	v_add_u32_e32 v4, v2, v4
	v_lshlrev_b32_e32 v6, 3, v3
	v_ashrrev_i32_e32 v5, 6, v4
	v_and_b32_e32 v6, -16, v6
	v_add_u32_e32 v6, v5, v6
	v_and_b32_e32 v5, 3, v5
	s_mov_b32 s0, 0x3fffe0
	v_lshrrev_b32_e32 v7, 2, v6
	v_lshlrev_b32_e32 v9, 1, v6
	v_and_b32_e32 v4, 0xc0, v4
	v_and_or_b32 v5, v6, s0, v5
	v_and_b32_e32 v7, 4, v7
	v_and_b32_e32 v9, 24, v9
	v_lshlrev_b32_e32 v3, 5, v3
	v_sub_u32_e32 v2, v2, v4
	v_or3_b32 v5, v5, v7, v9
	v_and_b32_e32 v3, 32, v3
	v_ashrrev_i16_sdwa v2, v195, sext(v2) dst_sel:DWORD dst_unused:UNUSED_PAD src0_sel:DWORD src1_sel:BYTE_0
	s_movk_i32 s1, 0xc00
	v_mul_u32_u24_e32 v5, 0xc00, v5
	v_add_u32_sdwa v2, v3, sext(v2) dst_sel:DWORD dst_unused:UNUSED_PAD src0_sel:DWORD src1_sel:WORD_0
	v_mul_lo_u32 v3, v6, s1
	v_add_lshl_u32 v140, v5, v2, 1
	v_add_lshl_u32 v142, v2, v3, 1
	v_bfe_i32 v2, v0, 27, 1
	v_lshrrev_b32_e32 v2, 22, v2
	v_add_u32_e32 v2, v1, v2
	v_and_b32_e32 v2, 0xfffffc00, v2
	v_sub_u32_e32 v1, v1, v2
	v_lshrrev_b32_e32 v2, 4, v1
	v_bitop3_b32 v1, v2, v1, 32 bitop3:0x6c
	v_ashrrev_i32_e32 v4, 31, v0
	v_ashrrev_i32_e32 v2, 31, v1
	v_lshrrev_b32_e32 v4, 26, v4
	v_lshrrev_b32_e32 v2, 26, v2
	v_add_u32_e32 v0, v0, v4
	v_add_u32_e32 v2, v1, v2
	v_ashrrev_i32_e32 v0, 6, v0
	s_add_u32 s79, s14, 0x31843000
	v_ashrrev_i32_e32 v3, 6, v2
	v_lshlrev_b32_e32 v4, 3, v0
	v_and_b32_e32 v2, 0xc0, v2
	s_addc_u32 s80, s15, 0
	v_and_b32_e32 v4, -16, v4
	v_lshlrev_b32_e32 v0, 5, v0
	v_sub_u32_e32 v1, v1, v2
	s_add_u32 s81, s14, 0x4243000
	v_add_u32_e32 v4, v3, v4
	v_and_b32_e32 v0, 32, v0
	v_ashrrev_i16_sdwa v1, v195, sext(v1) dst_sel:DWORD dst_unused:UNUSED_PAD src0_sel:DWORD src1_sel:BYTE_0
	s_addc_u32 s82, s15, 0
	s_ashr_i32 s19, s18, 6
	v_and_b32_e32 v3, 3, v3
	v_lshrrev_b32_e32 v5, 2, v4
	v_lshlrev_b32_e32 v6, 1, v4
	v_add_u32_sdwa v0, v0, sext(v1) dst_sel:DWORD dst_unused:UNUSED_PAD src0_sel:DWORD src1_sel:WORD_0
	v_mul_lo_u32 v1, v4, s1
	v_readlane_b32 s1, v254, 29
	s_ashr_i32 s22, s18, 8
	s_lshl_b32 s59, s19, 10
	v_and_or_b32 v3, v4, s0, v3
	v_and_b32_e32 v5, 4, v5
	v_and_b32_e32 v6, 24, v6
	s_mul_i32 s0, s1, 0x180000
	v_or3_b32 v3, v3, v5, v6
	s_add_u32 s12, s81, s0
	s_mul_hi_i32 s0, s1, 0x180000
	v_mul_u32_u24_e32 v3, 0xc00, v3
	s_addc_u32 s13, s82, s0
	s_add_i32 s65, s59, 0
	v_add_lshl_u32 v144, v3, v0, 1
	s_add_i32 m0, s65, 0x10000
	v_add_lshl_u32 v146, v0, v1, 1
	global_load_lds_dwordx4 v144, s[12:13]
	s_add_i32 m0, s65, 0x12000
	s_add_u32 s0, s12, 0xc0000
	global_load_lds_dwordx4 v140, s[12:13]
	s_addc_u32 s1, s13, 0
	s_add_i32 m0, s65, 0x14000
	v_mov_b32_e32 v145, v97
	global_load_lds_dwordx4 v144, s[0:1]
	s_add_i32 m0, s65, 0x16000
	v_mov_b32_e32 v141, v97
	global_load_lds_dwordx4 v140, s[0:1]
	v_readlane_b32 s0, v254, 53
	v_readlane_b32 s1, v254, 54
	s_mov_b32 s24, s0
	s_mul_i32 s0, s0, 0x180000
	s_add_u32 s0, s79, s0
	s_mul_hi_i32 s1, s24, 0x180000
	s_addc_u32 s1, s80, s1
	s_add_i32 s56, s65, 0x2000
	s_mov_b32 m0, s65
	s_add_u32 s24, s0, 0xc0000
	global_load_lds_dwordx4 v146, s[0:1]
	s_mov_b32 m0, s56
	s_addc_u32 s25, s1, 0
	s_add_i32 s54, s65, 0x4000
	global_load_lds_dwordx4 v142, s[0:1]
	s_mov_b32 m0, s54
	s_add_i32 s55, s65, 0x6000
	global_load_lds_dwordx4 v146, s[24:25]
	s_mov_b32 m0, s55
	s_cmp_eq_u32 s22, 1
	global_load_lds_dwordx4 v142, s[24:25]
	s_cselect_b64 s[24:25], -1, 0
	v_mov_b32_e32 v147, v97
	v_mov_b32_e32 v143, v97
	v_writelane_b32 v255, s24, 54
	v_lshl_add_u64 v[4:5], s[12:13], 0, v[144:145]
	v_lshl_add_u64 v[2:3], s[12:13], 0, v[140:141]
	v_lshl_add_u64 v[0:1], s[0:1], 0, v[146:147]
	v_writelane_b32 v255, s25, 55
	s_cmp_lg_u32 s22, 1
	v_lshl_add_u64 v[6:7], s[0:1], 0, v[142:143]
	s_cbranch_scc1 .LBB0_945
	s_barrier

.LBB0_1059:
	v_mbcnt_lo_u32_b32 v0, -1, 0
	v_mbcnt_hi_u32_b32 v0, -1, v0
	s_waitcnt vmcnt(0)
	v_readlane_b32 s0, v253, 11
	s_waitcnt lgkmcnt(0)
	s_barrier
	v_cmp_eq_u32_e32 vcc, s0, v0
	s_and_saveexec_b64 s[0:1], vcc
	v_readlane_b32 s42, v255, 50
	v_readlane_b32 s43, v255, 51
	s_cbranch_execz .LBB0_1111
	s_waitcnt vmcnt(0) expcnt(0) lgkmcnt(0)
	v_mov_b32_e32 v0, 0x20000
	ds_read2_b32 v[4:5], v0 offset1:1
	v_readlane_b32 s14, v254, 8
	v_readlane_b32 s15, v254, 9
	v_mov_b32_e32 v1, 1
	s_nop 4
	global_atomic_add v2, v97, v1, s[14:15] sc0
	s_waitcnt vmcnt(0) lgkmcnt(0)
	v_cvt_f32_u32_e32 v6, v2
	v_cvt_f32_u32_e32 v7, v4
	v_add_f32_e32 v6, 0.5, v6
	v_rcp_f32_e32 v7, v7
	s_nop 0
	v_mul_f32_e32 v6, v6, v7
	v_cvt_u32_f32_e32 v6, v6
	v_add_u32_e32 v7, 1, v6
	v_mul_lo_u32 v7, v7, v4
	v_add_u32_e32 v8, 1, v2
	v_cmp_eq_u32_e32 vcc, v7, v8
	s_cbranch_vccz .Lxb_g6_wait
	buffer_wbl2 sc1
	v_readlane_b32 s14, v254, 12
	v_readlane_b32 s15, v254, 13
	s_waitcnt vmcnt(0)
	s_nop 4
	global_atomic_add v9, v97, v1, s[14:15] sc0
	s_waitcnt vmcnt(0)
	v_cvt_f32_u32_e32 v10, v9
	v_cvt_f32_u32_e32 v11, v5
	v_add_f32_e32 v10, 0.5, v10
	v_rcp_f32_e32 v11, v11
	s_nop 0
	v_mul_f32_e32 v10, v10, v11
	v_cvt_u32_f32_e32 v10, v10
	v_add_u32_e32 v10, 1, v10
	v_mul_lo_u32 v10, v10, v5
	v_add_u32_e32 v9, 1, v9
	v_cmp_eq_u32_e32 vcc, v10, v9
	s_cbranch_vccz .Lxb_g6_wait
	v_readlane_b32 s14, v254, 14
	v_readlane_b32 s15, v254, 15
	s_mov_b64 s[18:19], exec
	s_mov_b64 exec, 0xffff
	s_nop 1
	v_mbcnt_lo_u32_b32 v10, -1, 0
	v_mov_b32_e32 v11, 1
	v_lshlrev_b32_e32 v10, 8, v10
	v_add_u32_e32 v10, 0x2000, v10
	global_atomic_add v10, v11, s[68:69]
	s_mov_b64 exec, s[18:19]
	s_nop 1
	global_atomic_add v97, v1, s[14:15]
	s_branch .Lxb_g6_acq

.LBB0_1131:
	v_mbcnt_lo_u32_b32 v0, -1, 0
	v_mbcnt_hi_u32_b32 v0, -1, v0
	s_waitcnt vmcnt(0)
	v_readlane_b32 s0, v253, 11
	s_barrier
	s_nop 0
	v_cmp_eq_u32_e32 vcc, s0, v0
	s_and_saveexec_b64 s[0:1], vcc
	s_xor_b64 s[0:1], exec, s[0:1]
	s_cbranch_execz .LBB0_1184
	s_waitcnt vmcnt(0) expcnt(0) lgkmcnt(0)
	v_mov_b32_e32 v0, 0x20000
	ds_read2_b32 v[4:5], v0 offset1:1
	v_readlane_b32 s14, v254, 8
	v_readlane_b32 s15, v254, 9
	v_mov_b32_e32 v1, 1
	s_nop 4
	global_atomic_add v2, v97, v1, s[14:15] sc0
	s_waitcnt vmcnt(0) lgkmcnt(0)
	v_cvt_f32_u32_e32 v6, v2
	v_cvt_f32_u32_e32 v7, v4
	v_add_f32_e32 v6, 0.5, v6
	v_rcp_f32_e32 v7, v7
	s_nop 0
	v_mul_f32_e32 v6, v6, v7
	v_cvt_u32_f32_e32 v6, v6
	v_add_u32_e32 v7, 1, v6
	v_mul_lo_u32 v7, v7, v4
	v_add_u32_e32 v8, 1, v2
	v_cmp_eq_u32_e32 vcc, v7, v8
	s_cbranch_vccz .Lxb_g7_wait
	buffer_wbl2 sc1
	v_readlane_b32 s14, v254, 12
	v_readlane_b32 s15, v254, 13
	s_waitcnt vmcnt(0)
	s_nop 4
	global_atomic_add v9, v97, v1, s[14:15] sc0
	s_waitcnt vmcnt(0)
	v_cvt_f32_u32_e32 v10, v9
	v_cvt_f32_u32_e32 v11, v5
	v_add_f32_e32 v10, 0.5, v10
	v_rcp_f32_e32 v11, v11
	s_nop 0
	v_mul_f32_e32 v10, v10, v11
	v_cvt_u32_f32_e32 v10, v10
	v_add_u32_e32 v10, 1, v10
	v_mul_lo_u32 v10, v10, v5
	v_add_u32_e32 v9, 1, v9
	v_cmp_eq_u32_e32 vcc, v10, v9
	s_cbranch_vccz .Lxb_g7_wait
	v_readlane_b32 s14, v254, 14
	v_readlane_b32 s15, v254, 15
	s_mov_b64 s[18:19], exec
	s_mov_b64 exec, 0xffff
	s_nop 1
	v_mbcnt_lo_u32_b32 v10, -1, 0
	v_mov_b32_e32 v11, 1
	v_lshlrev_b32_e32 v10, 8, v10
	v_add_u32_e32 v10, 0x2000, v10
	global_atomic_add v10, v11, s[68:69]
	s_mov_b64 exec, s[18:19]
	s_nop 1
	global_atomic_add v97, v1, s[14:15]
	s_branch .Lxb_g7_acq
